# attention epilogue gate loads without nt hint
# baseline (speedup 1.0000x reference)
; DI unsigned short f2bf(float f) { return (unsigned short)(cvtpk(f, f) & 0xffffu); }
; DI int crow(int r, int hi) { return (r & 3) + 8 * (r >> 2) + 4 * hi; }
; DI void attn_item(const bf16_t* __restrict__ Qw_, const bf16_t* __restrict__ Kh, const bf16_t* __restrict__ Vh, const bf16_t* Gw, bf16_t* Ow,
;                   int NT, int kt0, int qw, float sinkv, char* lds) {
;     ...
;     if (hi == 0) li_l[r32] = l_reg; asm volatile("s_waitcnt lgkmcnt(0)" ::: "memory");
;     bf16_t* OT = (bf16_t*)(lds + 67584 + wid * 8704);
; #pragma unroll
;     for (int r = 0; r < 16; ++r) { const int orow = crow(r, hi); const float rl = __builtin_amdgcn_rcpf(li_l[orow]);
; #pragma unroll
;         for (int d0 = 0; d0 < 4; ++d0) OT[orow * 136 + d0 * 32 + r32] = f2bf(o[d0][r] * rl); }
.LBB0_237:
	s_or_b64 exec, exec, s[4:5]
	s_waitcnt lgkmcnt(0)
	v_lshl_add_u32 v0, v193, 2, s54
	s_lshl_b64 s[4:5], s[14:15], 12
	ds_read_b32 v67, v0
	s_add_u32 s4, s23, s4
	s_addc_u32 s5, s30, s5
	s_lshl_b32 s14, s53, 1
	s_add_u32 s4, s4, s14
	s_addc_u32 s5, s5, 0
	s_lshr_b32 s14, s52, 6
	s_mulk_i32 s14, 0x2200
	s_waitcnt lgkmcnt(0)
	v_rcp_f32_e32 v67, v67
	s_add_i32 s14, s14, 0
	s_add_i32 s14, s14, 0x10800
	v_lshl_add_u32 v68, v188, 1, s14
	v_add_u32_e32 v69, v68, v196
	v_mul_f32_e32 v50, v50, v67
	v_mul_f32_e32 v34, v34, v67
	v_mul_f32_e32 v18, v18, v67
	v_cvt_pk_bf16_f32 v50, v50, v50
	ds_write_b16 v69, v50
	v_cvt_pk_bf16_f32 v34, v34, v34
	ds_write_b16 v69, v34 offset:64
	v_cvt_pk_bf16_f32 v18, v18, v18
	v_mul_f32_e32 v2, v2, v67
	ds_write_b16 v69, v18 offset:128
	v_cvt_pk_bf16_f32 v2, v2, v2
	ds_read_b32 v18, v0 offset:4
	ds_write_b16 v69, v2 offset:192
	v_add_u32_e32 v2, v68, v197
	s_waitcnt lgkmcnt(1)
	v_rcp_f32_e32 v18, v18
	s_nop 0
	v_mul_f32_e32 v34, v51, v18
	v_cvt_pk_bf16_f32 v34, v34, v34
	ds_write_b16 v2, v34
	v_mul_f32_e32 v34, v35, v18
	v_mul_f32_e32 v19, v19, v18
	v_mul_f32_e32 v3, v3, v18
	v_cvt_pk_bf16_f32 v34, v34, v34
	ds_write_b16 v2, v34 offset:64
	v_cvt_pk_bf16_f32 v19, v19, v19
	ds_write_b16 v2, v19 offset:128
	v_cvt_pk_bf16_f32 v3, v3, v3
	ds_read_b32 v18, v0 offset:8
	ds_write_b16 v2, v3 offset:192
	s_waitcnt lgkmcnt(1)
	v_rcp_f32_e32 v18, v18
	s_nop 0
	v_mul_f32_e32 v3, v52, v18
	v_cvt_pk_bf16_f32 v3, v3, v3
	ds_write_b16 v2, v3 offset:272
	v_mul_f32_e32 v3, v36, v18
	v_cvt_pk_bf16_f32 v3, v3, v3
	ds_write_b16 v2, v3 offset:336
	v_mul_f32_e32 v3, v20, v18
	v_cvt_pk_bf16_f32 v3, v3, v3
	ds_write_b16 v2, v3 offset:400
	v_mul_f32_e32 v3, v4, v18
	v_cvt_pk_bf16_f32 v3, v3, v3
	ds_read_b32 v4, v0 offset:12
	ds_write_b16 v2, v3 offset:464
	s_waitcnt lgkmcnt(1)
	v_rcp_f32_e32 v4, v4
	s_nop 0
	v_mul_f32_e32 v3, v53, v4
	v_cvt_pk_bf16_f32 v3, v3, v3
	ds_write_b16 v2, v3 offset:544
	v_mul_f32_e32 v3, v37, v4
	v_cvt_pk_bf16_f32 v3, v3, v3
	ds_write_b16 v2, v3 offset:608
	v_mul_f32_e32 v3, v21, v4
	v_cvt_pk_bf16_f32 v3, v3, v3
	ds_write_b16 v2, v3 offset:672
	v_mul_f32_e32 v3, v5, v4
	v_cvt_pk_bf16_f32 v3, v3, v3
	ds_read_b32 v4, v0 offset:32
	ds_write_b16 v2, v3 offset:736
	s_waitcnt lgkmcnt(1)
	v_rcp_f32_e32 v4, v4
	s_nop 0
	v_mul_f32_e32 v3, v54, v4
	v_cvt_pk_bf16_f32 v3, v3, v3
	ds_write_b16 v2, v3 offset:1904
	v_mul_f32_e32 v3, v38, v4
	v_cvt_pk_bf16_f32 v3, v3, v3
	ds_write_b16 v2, v3 offset:1968
	v_mul_f32_e32 v3, v22, v4
	v_cvt_pk_bf16_f32 v3, v3, v3
	ds_write_b16 v2, v3 offset:2032
	v_mul_f32_e32 v3, v6, v4
	v_cvt_pk_bf16_f32 v3, v3, v3
	ds_read_b32 v4, v0 offset:36
	ds_write_b16 v2, v3 offset:2096
	s_waitcnt lgkmcnt(1)
	v_rcp_f32_e32 v4, v4
	s_nop 0
	v_mul_f32_e32 v3, v55, v4
	v_cvt_pk_bf16_f32 v3, v3, v3
	ds_write_b16 v2, v3 offset:2176
	v_mul_f32_e32 v3, v39, v4
	v_cvt_pk_bf16_f32 v3, v3, v3
	ds_write_b16 v2, v3 offset:2240
	v_mul_f32_e32 v3, v23, v4
	v_cvt_pk_bf16_f32 v3, v3, v3
	ds_write_b16 v2, v3 offset:2304
	v_mul_f32_e32 v3, v7, v4
	v_cvt_pk_bf16_f32 v3, v3, v3
	ds_read_b32 v4, v0 offset:40
	ds_write_b16 v2, v3 offset:2368
	v_add_u32_e32 v3, v68, v198
	s_waitcnt lgkmcnt(1)
	v_rcp_f32_e32 v4, v4
	s_nop 0
	v_mul_f32_e32 v5, v56, v4
	v_cvt_pk_bf16_f32 v5, v5, v5
	ds_write_b16 v2, v5 offset:2448
	v_mul_f32_e32 v2, v40, v4
	v_cvt_pk_bf16_f32 v2, v2, v2
	ds_write_b16 v3, v2 offset:64
	v_mul_f32_e32 v2, v24, v4
	v_cvt_pk_bf16_f32 v2, v2, v2
	ds_write_b16 v3, v2 offset:128
	v_mul_f32_e32 v2, v8, v4
	v_cvt_pk_bf16_f32 v2, v2, v2
	ds_read_b32 v4, v0 offset:44
	ds_write_b16 v3, v2 offset:192
	s_waitcnt lgkmcnt(1)
	v_rcp_f32_e32 v4, v4
	s_nop 0
	v_mul_f32_e32 v2, v57, v4
	v_cvt_pk_bf16_f32 v2, v2, v2
	ds_write_b16 v3, v2 offset:272
	v_mul_f32_e32 v2, v41, v4
	v_cvt_pk_bf16_f32 v2, v2, v2
	ds_write_b16 v3, v2 offset:336
	v_mul_f32_e32 v2, v25, v4
	v_cvt_pk_bf16_f32 v2, v2, v2
	ds_write_b16 v3, v2 offset:400
	v_mul_f32_e32 v2, v9, v4
	v_cvt_pk_bf16_f32 v2, v2, v2
	ds_read_b32 v4, v0 offset:64
	ds_write_b16 v3, v2 offset:464
	s_waitcnt lgkmcnt(1)
	v_rcp_f32_e32 v4, v4
	s_nop 0
	v_mul_f32_e32 v2, v58, v4
	v_cvt_pk_bf16_f32 v2, v2, v2
	ds_write_b16 v3, v2 offset:1632
	v_mul_f32_e32 v2, v42, v4
	v_cvt_pk_bf16_f32 v2, v2, v2
	ds_write_b16 v3, v2 offset:1696
	v_mul_f32_e32 v2, v26, v4
	v_cvt_pk_bf16_f32 v2, v2, v2
	ds_write_b16 v3, v2 offset:1760
	v_mul_f32_e32 v2, v10, v4
	v_cvt_pk_bf16_f32 v2, v2, v2
	ds_read_b32 v4, v0 offset:68
	ds_write_b16 v3, v2 offset:1824
	s_waitcnt lgkmcnt(1)
	v_rcp_f32_e32 v4, v4
	s_nop 0
	v_mul_f32_e32 v2, v59, v4
	v_cvt_pk_bf16_f32 v2, v2, v2
	ds_write_b16 v3, v2 offset:1904
	v_mul_f32_e32 v2, v43, v4
	v_cvt_pk_bf16_f32 v2, v2, v2
	ds_write_b16 v3, v2 offset:1968
	v_mul_f32_e32 v2, v27, v4
	v_cvt_pk_bf16_f32 v2, v2, v2
	ds_write_b16 v3, v2 offset:2032
	v_mul_f32_e32 v2, v11, v4
	v_cvt_pk_bf16_f32 v2, v2, v2
	ds_read_b32 v4, v0 offset:72
	ds_write_b16 v3, v2 offset:2096
	s_waitcnt lgkmcnt(1)
	v_rcp_f32_e32 v4, v4
	s_nop 0
	v_mul_f32_e32 v2, v60, v4
	v_cvt_pk_bf16_f32 v2, v2, v2
	ds_write_b16 v3, v2 offset:2176
	v_mul_f32_e32 v2, v44, v4
	v_cvt_pk_bf16_f32 v2, v2, v2
	ds_write_b16 v3, v2 offset:2240
	v_mul_f32_e32 v2, v28, v4
	v_cvt_pk_bf16_f32 v2, v2, v2
	ds_write_b16 v3, v2 offset:2304
	v_mul_f32_e32 v2, v12, v4
	v_cvt_pk_bf16_f32 v2, v2, v2
	ds_read_b32 v4, v0 offset:76
	ds_write_b16 v3, v2 offset:2368
	s_waitcnt lgkmcnt(1)
	v_rcp_f32_e32 v4, v4
	s_nop 0
	v_mul_f32_e32 v2, v61, v4
	v_cvt_pk_bf16_f32 v2, v2, v2
	ds_write_b16 v3, v2 offset:2448
	v_mul_f32_e32 v2, v45, v4
	v_cvt_pk_bf16_f32 v2, v2, v2
	ds_write_b16 v3, v2 offset:2512
	v_mul_f32_e32 v2, v29, v4
	v_cvt_pk_bf16_f32 v2, v2, v2
	ds_write_b16 v3, v2 offset:2576
	v_mul_f32_e32 v2, v13, v4
	v_cvt_pk_bf16_f32 v2, v2, v2
	ds_read_b32 v4, v0 offset:96
	ds_write_b16 v3, v2 offset:2640
	s_waitcnt lgkmcnt(1)
; DI unsigned cvtpk(float lo, float hi) { unsigned r; asm volatile("v_cvt_pk_bf16_f32 %0, %1, %2" : "=v"(r) : "v"(lo), "v"(hi)); return r; }
; DI float bflo(unsigned w) { return __uint_as_float(w << 16); }
; DI float bfhi(unsigned w) { return __uint_as_float(w & 0xffff0000u); }
; DI unsigned short f2bf(float f) { return (unsigned short)(cvtpk(f, f) & 0xffffu); }
; DI float sigm(float x) { return rcpf_(1.f + ex2(-x * LOG2E)); }
; DI int crow(int r, int hi) { return (r & 3) + 8 * (r >> 2) + 4 * hi; }
; DI void attn_item(const bf16_t* __restrict__ Qw_, const bf16_t* __restrict__ Kh, const bf16_t* __restrict__ Vh, const bf16_t* Gw, bf16_t* Ow,
;                   int NT, int kt0, int qw, float sinkv, char* lds) {
;     ...
;     for (int r = 0; r < 16; ++r) { const int orow = crow(r, hi); const float rl = __builtin_amdgcn_rcpf(li_l[orow]);
; #pragma unroll
;         for (int d0 = 0; d0 < 4; ++d0) OT[orow * 136 + d0 * 32 + r32] = f2bf(o[d0][r] * rl); }
;     __builtin_amdgcn_sched_barrier(0);
;     u32x4 gv[8];
; #pragma unroll
;     for (int k = 0; k < 8; ++k) gv[k] = __builtin_nontemporal_load((const u32x4*)(Gw + (size_t)(er + 4 * k) * 2048 + ec * 8));
;     asm volatile("s_waitcnt lgkmcnt(0)" ::: "memory");
; #pragma unroll
;     for (int k = 0; k < 8; ++k) {
;         const u32x4 ov = *(const u32x4*)(OT + (er + 4 * k) * 136 + ec * 8); u32x4 w;
; #pragma unroll
;         for (int i = 0; i < 4; ++i) { const float g0 = bflo(gv[k][i]), g1 = bfhi(gv[k][i]); w[i] = cvtpk(bflo(ov[i]) * g0 * sigm(g0), bfhi(ov[i]) * g1 * sigm(g1)); }
;         __builtin_nontemporal_store(w, (u32x4*)(Ow + (size_t)(er + 4 * k) * 2048 + ec * 8));
	v_rcp_f32_e32 v4, v4
	s_nop 0
	v_mul_f32_e32 v2, v62, v4
	v_cvt_pk_bf16_f32 v2, v2, v2
	ds_write_b16 v3, v2 offset:3808
	v_mul_f32_e32 v2, v46, v4
	v_cvt_pk_bf16_f32 v2, v2, v2
	ds_write_b16 v3, v2 offset:3872
	v_mul_f32_e32 v2, v30, v4
	v_cvt_pk_bf16_f32 v2, v2, v2
	ds_write_b16 v3, v2 offset:3936
	v_mul_f32_e32 v2, v14, v4
	v_cvt_pk_bf16_f32 v2, v2, v2
	ds_read_b32 v4, v0 offset:100
	ds_write_b16 v3, v2 offset:4000
	s_waitcnt lgkmcnt(1)
	v_rcp_f32_e32 v4, v4
	s_nop 0
	v_mul_f32_e32 v2, v63, v4
	v_cvt_pk_bf16_f32 v2, v2, v2
	ds_write_b16 v3, v2 offset:4080
	v_mul_f32_e32 v2, v47, v4
	v_cvt_pk_bf16_f32 v2, v2, v2
	ds_write_b16 v3, v2 offset:4144
	v_mul_f32_e32 v2, v31, v4
	v_cvt_pk_bf16_f32 v2, v2, v2
	ds_write_b16 v3, v2 offset:4208
	v_mul_f32_e32 v2, v15, v4
	v_cvt_pk_bf16_f32 v2, v2, v2
	ds_read_b32 v4, v0 offset:104
	ds_write_b16 v3, v2 offset:4272
	s_waitcnt lgkmcnt(1)
	v_rcp_f32_e32 v4, v4
	s_nop 0
	v_mul_f32_e32 v2, v64, v4
	v_cvt_pk_bf16_f32 v2, v2, v2
	ds_write_b16 v3, v2 offset:4352
	v_mul_f32_e32 v2, v48, v4
	v_cvt_pk_bf16_f32 v2, v2, v2
	ds_write_b16 v3, v2 offset:4416
	v_mul_f32_e32 v2, v32, v4
	v_cvt_pk_bf16_f32 v2, v2, v2
	ds_write_b16 v3, v2 offset:4480
	v_mul_f32_e32 v2, v16, v4
	v_cvt_pk_bf16_f32 v4, v2, v2
	ds_read_b32 v0, v0 offset:108
	ds_write_b16 v3, v4 offset:4544
	v_ashrrev_i32_e32 v2, 4, v66
	s_waitcnt lgkmcnt(1)
	v_rcp_f32_e32 v0, v0
	s_nop 0
	v_mul_f32_e32 v4, v65, v0
	v_cvt_pk_bf16_f32 v4, v4, v4
	ds_write_b16 v3, v4 offset:4624
	v_mul_f32_e32 v4, v49, v0
	v_cvt_pk_bf16_f32 v4, v4, v4
	ds_write_b16 v3, v4 offset:4688
	v_mul_f32_e32 v4, v33, v0
	v_mul_f32_e32 v0, v17, v0
	v_cvt_pk_bf16_f32 v4, v4, v4
	ds_write_b16 v3, v4 offset:4752
	v_cvt_pk_bf16_f32 v0, v0, v0
	ds_write_b16 v3, v0 offset:4816
	v_lshlrev_b32_e32 v0, 4, v66
	v_and_b32_e32 v0, 0xf0, v0
	v_ashrrev_i32_e32 v3, 31, v2
	v_lshl_add_u64 v[4:5], s[4:5], 0, v[0:1]
	v_lshlrev_b64 v[6:7], 12, v[2:3]
	v_lshl_add_u64 v[50:51], v[4:5], 0, v[6:7]
	global_load_dwordx4 v[38:41], v[50:51], off
	v_add_co_u32_e32 v52, vcc, s38, v50
	v_mul_lo_u32 v2, v2, s39
	s_nop 0
	v_addc_co_u32_e32 v53, vcc, 0, v51, vcc
	v_add_co_u32_e32 v36, vcc, s47, v50
	v_add3_u32 v0, s14, v0, v2
	s_nop 0
	v_addc_co_u32_e32 v37, vcc, 0, v51, vcc
	v_add_co_u32_e32 v34, vcc, s48, v50
	s_add_i32 s51, s51, s24
	s_nop 0
	v_addc_co_u32_e32 v35, vcc, 0, v51, vcc
	v_add_co_u32_e32 v32, vcc, s42, v50
	s_cmpk_lt_i32 s51, 0x400
	s_nop 0
	v_addc_co_u32_e32 v33, vcc, 0, v51, vcc
	v_add_co_u32_e32 v30, vcc, s49, v50
	s_waitcnt vmcnt(0)
	v_lshlrev_b32_e32 v57, 16, v38
	v_addc_co_u32_e32 v31, vcc, 0, v51, vcc
	v_add_co_u32_e32 v28, vcc, s36, v50
	v_and_b32_e32 v38, 0xffff0000, v38
	s_nop 0
	v_addc_co_u32_e32 v29, vcc, 0, v51, vcc
	v_add_co_u32_e32 v26, vcc, s50, v50
	v_lshlrev_b32_e32 v58, 16, v39
	s_nop 0
	v_addc_co_u32_e32 v27, vcc, 0, v51, vcc
	global_load_dwordx4 v[42:45], v[52:53], off
	global_load_dwordx4 v[22:25], v[36:37], off
	global_load_dwordx4 v[18:21], v[34:35], off
	global_load_dwordx4 v[14:17], v[32:33], off
	global_load_dwordx4 v[10:13], v[30:31], off
	global_load_dwordx4 v[6:9], v[28:29], off
	global_load_dwordx4 v[2:5], v[26:27], off
	s_waitcnt lgkmcnt(0)
	ds_read_b128 v[46:49], v0
	v_and_b32_e32 v39, 0xffff0000, v39
	v_lshlrev_b32_e32 v59, 16, v40
	v_and_b32_e32 v40, 0xffff0000, v40
	s_waitcnt lgkmcnt(0)
	v_lshlrev_b32_e32 v54, 16, v46
	v_and_b32_e32 v46, 0xffff0000, v46
	v_lshlrev_b32_e32 v55, 16, v47
	v_and_b32_e32 v47, 0xffff0000, v47
	v_mul_f32_e32 v46, v46, v38
	v_mul_f32_e32 v38, 0xbfb8aa3b, v38
	v_mul_f32_e32 v55, v55, v58
	v_mul_f32_e32 v58, 0xbfb8aa3b, v58
	v_mul_f32_e32 v47, v47, v39
	v_mul_f32_e32 v39, 0xbfb8aa3b, v39
	v_lshlrev_b32_e32 v56, 16, v48
	v_and_b32_e32 v48, 0xffff0000, v48
	v_mul_f32_e32 v54, v54, v57
	v_mul_f32_e32 v57, 0xbfb8aa3b, v57
	v_exp_f32_e32 v38, v38
	v_exp_f32_e32 v58, v58
	v_exp_f32_e32 v39, v39
	v_mul_f32_e32 v48, v48, v40
	v_mul_f32_e32 v40, 0xbfb8aa3b, v40
	v_exp_f32_e32 v57, v57
	v_exp_f32_e32 v40, v40
	v_add_f32_e32 v38, 1.0, v38
	v_add_f32_e32 v58, 1.0, v58
	v_add_f32_e32 v39, 1.0, v39
	v_add_f32_e32 v57, 1.0, v57
	v_rcp_f32_e32 v38, v38
	v_rcp_f32_e32 v58, v58
	v_rcp_f32_e32 v39, v39
	v_mul_f32_e32 v56, v56, v59
	v_mul_f32_e32 v59, 0xbfb8aa3b, v59
	v_add_f32_e32 v40, 1.0, v40
	v_rcp_f32_e32 v57, v57
	v_exp_f32_e32 v59, v59
	v_rcp_f32_e32 v40, v40
	v_mul_f32_e32 v38, v38, v46
	v_mul_f32_e32 v46, v58, v55
	v_mul_f32_e32 v39, v39, v47
	v_mul_f32_e32 v54, v57, v54
	v_cvt_pk_bf16_f32 v38, v54, v38
	v_cvt_pk_bf16_f32 v39, v46, v39
	v_lshlrev_b32_e32 v46, 16, v41
	v_add_f32_e32 v59, 1.0, v59
	v_mul_f32_e32 v40, v40, v48
	v_mul_f32_e32 v48, 0xbfb8aa3b, v46
	v_rcp_f32_e32 v59, v59
	v_exp_f32_e32 v48, v48
	v_and_b32_e32 v41, 0xffff0000, v41
	v_mul_f32_e32 v54, 0xbfb8aa3b, v41
	v_exp_f32_e32 v54, v54
	v_mul_f32_e32 v47, v59, v56
	v_add_f32_e32 v48, 1.0, v48
	v_cvt_pk_bf16_f32 v40, v47, v40
	v_lshlrev_b32_e32 v47, 16, v49
	v_rcp_f32_e32 v48, v48
	v_mul_f32_e32 v46, v47, v46
	v_add_f32_e32 v47, 1.0, v54
	v_rcp_f32_e32 v47, v47
	v_mul_f32_e32 v46, v48, v46
	v_and_b32_e32 v48, 0xffff0000, v49
	v_mul_f32_e32 v41, v48, v41
	v_mul_f32_e32 v41, v47, v41
	v_cvt_pk_bf16_f32 v41, v46, v41
	global_store_dwordx4 v[50:51], v[38:41], off nt
	ds_read_b128 v[46:49], v0 offset:1088
	s_waitcnt vmcnt(7)
	v_lshlrev_b32_e32 v38, 16, v42
	v_mul_f32_e32 v40, 0xbfb8aa3b, v38
	v_exp_f32_e32 v40, v40
	v_and_b32_e32 v41, 0xffff0000, v42
	v_mul_f32_e32 v42, 0xbfb8aa3b, v41
	v_exp_f32_e32 v42, v42
	v_add_f32_e32 v40, 1.0, v40
	s_waitcnt lgkmcnt(0)
; DI unsigned cvtpk(float lo, float hi) { unsigned r; asm volatile("v_cvt_pk_bf16_f32 %0, %1, %2" : "=v"(r) : "v"(lo), "v"(hi)); return r; }
; DI float bflo(unsigned w) { return __uint_as_float(w << 16); }
; DI float bfhi(unsigned w) { return __uint_as_float(w & 0xffff0000u); }
; DI float sigm(float x) { return rcpf_(1.f + ex2(-x * LOG2E)); }
; DI void attn_item(const bf16_t* __restrict__ Qw_, const bf16_t* __restrict__ Kh, const bf16_t* __restrict__ Vh, const bf16_t* Gw, bf16_t* Ow,
;                   int NT, int kt0, int qw, float sinkv, char* lds) {
;     ...
; #pragma unroll
;     for (int k = 0; k < 8; ++k) {
;         const u32x4 ov = *(const u32x4*)(OT + (er + 4 * k) * 136 + ec * 8); u32x4 w;
; #pragma unroll
;         for (int i = 0; i < 4; ++i) { const float g0 = bflo(gv[k][i]), g1 = bfhi(gv[k][i]); w[i] = cvtpk(bflo(ov[i]) * g0 * sigm(g0), bfhi(ov[i]) * g1 * sigm(g1)); }
;         __builtin_nontemporal_store(w, (u32x4*)(Ow + (size_t)(er + 4 * k) * 2048 + ec * 8));
;     }
	v_lshlrev_b32_e32 v39, 16, v46
	v_rcp_f32_e32 v40, v40
	v_mul_f32_e32 v38, v39, v38
	v_add_f32_e32 v39, 1.0, v42
	v_rcp_f32_e32 v39, v39
	v_mul_f32_e32 v38, v40, v38
	v_and_b32_e32 v40, 0xffff0000, v46
	v_mul_f32_e32 v40, v40, v41
	v_mul_f32_e32 v39, v39, v40
	v_cvt_pk_bf16_f32 v38, v38, v39
	v_lshlrev_b32_e32 v39, 16, v43
	v_mul_f32_e32 v41, 0xbfb8aa3b, v39
	v_exp_f32_e32 v41, v41
	v_and_b32_e32 v42, 0xffff0000, v43
	v_mul_f32_e32 v43, 0xbfb8aa3b, v42
	v_exp_f32_e32 v43, v43
	v_add_f32_e32 v41, 1.0, v41
	v_lshlrev_b32_e32 v40, 16, v47
	v_rcp_f32_e32 v41, v41
	v_mul_f32_e32 v39, v40, v39
	v_add_f32_e32 v40, 1.0, v43
	v_rcp_f32_e32 v40, v40
	v_mul_f32_e32 v39, v41, v39
	v_and_b32_e32 v41, 0xffff0000, v47
	v_mul_f32_e32 v41, v41, v42
	v_mul_f32_e32 v40, v40, v41
	v_cvt_pk_bf16_f32 v39, v39, v40
	v_lshlrev_b32_e32 v40, 16, v44
	v_mul_f32_e32 v42, 0xbfb8aa3b, v40
	v_exp_f32_e32 v42, v42
	v_and_b32_e32 v43, 0xffff0000, v44
	v_mul_f32_e32 v44, 0xbfb8aa3b, v43
	v_exp_f32_e32 v44, v44
	v_add_f32_e32 v42, 1.0, v42
	v_lshlrev_b32_e32 v41, 16, v48
	v_rcp_f32_e32 v42, v42
	v_mul_f32_e32 v40, v41, v40
	v_add_f32_e32 v41, 1.0, v44
	v_rcp_f32_e32 v41, v41
	v_mul_f32_e32 v40, v42, v40
	v_and_b32_e32 v42, 0xffff0000, v48
	v_mul_f32_e32 v42, v42, v43
	v_mul_f32_e32 v41, v41, v42
	v_cvt_pk_bf16_f32 v40, v40, v41
	v_lshlrev_b32_e32 v41, 16, v45
	v_mul_f32_e32 v43, 0xbfb8aa3b, v41
	v_exp_f32_e32 v43, v43
	v_and_b32_e32 v44, 0xffff0000, v45
	v_mul_f32_e32 v45, 0xbfb8aa3b, v44
	v_exp_f32_e32 v45, v45
	v_add_f32_e32 v43, 1.0, v43
	v_lshlrev_b32_e32 v42, 16, v49
	v_rcp_f32_e32 v43, v43
	v_mul_f32_e32 v41, v42, v41
	v_add_f32_e32 v42, 1.0, v45
	v_rcp_f32_e32 v42, v42
	v_mul_f32_e32 v41, v43, v41
	v_and_b32_e32 v43, 0xffff0000, v49
	v_mul_f32_e32 v43, v43, v44
	v_mul_f32_e32 v42, v42, v43
	v_cvt_pk_bf16_f32 v41, v41, v42
	global_store_dwordx4 v[52:53], v[38:41], off nt
	ds_read_b128 v[42:45], v0 offset:2176
	s_waitcnt vmcnt(7)
	v_lshlrev_b32_e32 v38, 16, v22
	v_mul_f32_e32 v40, 0xbfb8aa3b, v38
	v_exp_f32_e32 v40, v40
	v_and_b32_e32 v22, 0xffff0000, v22
	v_mul_f32_e32 v41, 0xbfb8aa3b, v22
	v_exp_f32_e32 v41, v41
	v_add_f32_e32 v40, 1.0, v40
	s_waitcnt lgkmcnt(0)
	v_lshlrev_b32_e32 v39, 16, v42
	v_rcp_f32_e32 v40, v40
	v_mul_f32_e32 v38, v39, v38
	v_add_f32_e32 v39, 1.0, v41
	v_rcp_f32_e32 v39, v39
	v_mul_f32_e32 v38, v40, v38
	v_and_b32_e32 v40, 0xffff0000, v42
	v_mul_f32_e32 v22, v40, v22
	v_mul_f32_e32 v22, v39, v22
	v_cvt_pk_bf16_f32 v22, v38, v22
	v_lshlrev_b32_e32 v38, 16, v23
	v_mul_f32_e32 v40, 0xbfb8aa3b, v38
	v_exp_f32_e32 v40, v40
	v_and_b32_e32 v23, 0xffff0000, v23
	v_mul_f32_e32 v41, 0xbfb8aa3b, v23
	v_exp_f32_e32 v41, v41
	v_add_f32_e32 v40, 1.0, v40
	v_lshlrev_b32_e32 v39, 16, v43
	v_rcp_f32_e32 v40, v40
	v_mul_f32_e32 v38, v39, v38
	v_add_f32_e32 v39, 1.0, v41
	v_rcp_f32_e32 v39, v39
	v_mul_f32_e32 v38, v40, v38
	v_and_b32_e32 v40, 0xffff0000, v43
	v_mul_f32_e32 v23, v40, v23
	v_mul_f32_e32 v23, v39, v23
	v_cvt_pk_bf16_f32 v23, v38, v23
	v_lshlrev_b32_e32 v38, 16, v24
	v_mul_f32_e32 v40, 0xbfb8aa3b, v38
	v_exp_f32_e32 v40, v40
	v_and_b32_e32 v24, 0xffff0000, v24
	v_mul_f32_e32 v41, 0xbfb8aa3b, v24
	v_exp_f32_e32 v41, v41
	v_add_f32_e32 v40, 1.0, v40
	v_lshlrev_b32_e32 v39, 16, v44
	v_rcp_f32_e32 v40, v40
	v_mul_f32_e32 v38, v39, v38
	v_add_f32_e32 v39, 1.0, v41
	v_rcp_f32_e32 v39, v39
	v_mul_f32_e32 v38, v40, v38
	v_and_b32_e32 v40, 0xffff0000, v44
	v_mul_f32_e32 v24, v40, v24
	v_mul_f32_e32 v24, v39, v24
	v_cvt_pk_bf16_f32 v24, v38, v24
	v_lshlrev_b32_e32 v38, 16, v25
	v_mul_f32_e32 v40, 0xbfb8aa3b, v38
	v_exp_f32_e32 v40, v40
	v_and_b32_e32 v25, 0xffff0000, v25
	v_mul_f32_e32 v41, 0xbfb8aa3b, v25
	v_exp_f32_e32 v41, v41
	v_add_f32_e32 v40, 1.0, v40
	v_lshlrev_b32_e32 v39, 16, v45
	v_rcp_f32_e32 v40, v40
	v_mul_f32_e32 v38, v39, v38
	v_add_f32_e32 v39, 1.0, v41
	v_rcp_f32_e32 v39, v39
	v_mul_f32_e32 v38, v40, v38
	v_and_b32_e32 v40, 0xffff0000, v45
	v_mul_f32_e32 v25, v40, v25
	v_mul_f32_e32 v25, v39, v25
	v_cvt_pk_bf16_f32 v25, v38, v25
	global_store_dwordx4 v[36:37], v[22:25], off nt
	ds_read_b128 v[38:41], v0 offset:3264
	s_waitcnt vmcnt(7)
	v_lshlrev_b32_e32 v22, 16, v18
	v_mul_f32_e32 v24, 0xbfb8aa3b, v22
	v_exp_f32_e32 v24, v24
	v_and_b32_e32 v18, 0xffff0000, v18
	v_mul_f32_e32 v25, 0xbfb8aa3b, v18
	v_exp_f32_e32 v25, v25
	v_add_f32_e32 v24, 1.0, v24
	s_waitcnt lgkmcnt(0)
	v_lshlrev_b32_e32 v23, 16, v38
	v_rcp_f32_e32 v24, v24
	v_mul_f32_e32 v22, v23, v22
	v_add_f32_e32 v23, 1.0, v25
	v_rcp_f32_e32 v23, v23
	v_mul_f32_e32 v22, v24, v22
	v_and_b32_e32 v24, 0xffff0000, v38
	v_mul_f32_e32 v18, v24, v18
	v_mul_f32_e32 v18, v23, v18
	v_cvt_pk_bf16_f32 v18, v22, v18
	v_lshlrev_b32_e32 v22, 16, v19
	v_mul_f32_e32 v24, 0xbfb8aa3b, v22
	v_exp_f32_e32 v24, v24
	v_and_b32_e32 v19, 0xffff0000, v19
	v_mul_f32_e32 v25, 0xbfb8aa3b, v19
	v_exp_f32_e32 v25, v25
	v_add_f32_e32 v24, 1.0, v24
	v_lshlrev_b32_e32 v23, 16, v39
	v_rcp_f32_e32 v24, v24
	v_mul_f32_e32 v22, v23, v22
	v_add_f32_e32 v23, 1.0, v25
	v_rcp_f32_e32 v23, v23
	v_mul_f32_e32 v22, v24, v22
	v_and_b32_e32 v24, 0xffff0000, v39
	v_mul_f32_e32 v19, v24, v19
	v_mul_f32_e32 v19, v23, v19
	v_cvt_pk_bf16_f32 v19, v22, v19
	v_lshlrev_b32_e32 v22, 16, v20
	v_mul_f32_e32 v24, 0xbfb8aa3b, v22
	v_exp_f32_e32 v24, v24
	v_and_b32_e32 v20, 0xffff0000, v20
	v_mul_f32_e32 v25, 0xbfb8aa3b, v20
	v_exp_f32_e32 v25, v25
	v_add_f32_e32 v24, 1.0, v24
	v_lshlrev_b32_e32 v23, 16, v40
	v_rcp_f32_e32 v24, v24
	v_mul_f32_e32 v22, v23, v22
	v_add_f32_e32 v23, 1.0, v25
	v_rcp_f32_e32 v23, v23
	v_mul_f32_e32 v22, v24, v22
	v_and_b32_e32 v24, 0xffff0000, v40
	v_mul_f32_e32 v20, v24, v20
	v_mul_f32_e32 v20, v23, v20
	v_cvt_pk_bf16_f32 v20, v22, v20
	v_lshlrev_b32_e32 v22, 16, v21
	v_mul_f32_e32 v24, 0xbfb8aa3b, v22
	v_exp_f32_e32 v24, v24
	v_and_b32_e32 v21, 0xffff0000, v21
	v_mul_f32_e32 v25, 0xbfb8aa3b, v21
	v_exp_f32_e32 v25, v25
	v_add_f32_e32 v24, 1.0, v24
	v_lshlrev_b32_e32 v23, 16, v41
	v_rcp_f32_e32 v24, v24
	v_mul_f32_e32 v22, v23, v22
	v_add_f32_e32 v23, 1.0, v25
	v_rcp_f32_e32 v23, v23
	v_mul_f32_e32 v22, v24, v22
	v_and_b32_e32 v24, 0xffff0000, v41
	v_mul_f32_e32 v21, v24, v21
	v_mul_f32_e32 v21, v23, v21
	v_cvt_pk_bf16_f32 v21, v22, v21
	global_store_dwordx4 v[34:35], v[18:21], off nt
	ds_read_b128 v[22:25], v0 offset:4352
	s_waitcnt vmcnt(7)
; DI unsigned cvtpk(float lo, float hi) { unsigned r; asm volatile("v_cvt_pk_bf16_f32 %0, %1, %2" : "=v"(r) : "v"(lo), "v"(hi)); return r; }
; DI float bflo(unsigned w) { return __uint_as_float(w << 16); }
; DI float bfhi(unsigned w) { return __uint_as_float(w & 0xffff0000u); }
; DI float sigm(float x) { return rcpf_(1.f + ex2(-x * LOG2E)); }
; DI void attn_item(const bf16_t* __restrict__ Qw_, const bf16_t* __restrict__ Kh, const bf16_t* __restrict__ Vh, const bf16_t* Gw, bf16_t* Ow,
;                   int NT, int kt0, int qw, float sinkv, char* lds) {
;     ...
; #pragma unroll
;     for (int k = 0; k < 8; ++k) {
;         const u32x4 ov = *(const u32x4*)(OT + (er + 4 * k) * 136 + ec * 8); u32x4 w;
; #pragma unroll
;         for (int i = 0; i < 4; ++i) { const float g0 = bflo(gv[k][i]), g1 = bfhi(gv[k][i]); w[i] = cvtpk(bflo(ov[i]) * g0 * sigm(g0), bfhi(ov[i]) * g1 * sigm(g1)); }
;         __builtin_nontemporal_store(w, (u32x4*)(Ow + (size_t)(er + 4 * k) * 2048 + ec * 8));
;     }
	v_lshlrev_b32_e32 v18, 16, v14
	v_mul_f32_e32 v20, 0xbfb8aa3b, v18
	v_exp_f32_e32 v20, v20
	v_and_b32_e32 v14, 0xffff0000, v14
	v_mul_f32_e32 v21, 0xbfb8aa3b, v14
	v_exp_f32_e32 v21, v21
	v_add_f32_e32 v20, 1.0, v20
	s_waitcnt lgkmcnt(0)
	v_lshlrev_b32_e32 v19, 16, v22
	v_rcp_f32_e32 v20, v20
	v_mul_f32_e32 v18, v19, v18
	v_add_f32_e32 v19, 1.0, v21
	v_rcp_f32_e32 v19, v19
	v_mul_f32_e32 v18, v20, v18
	v_and_b32_e32 v20, 0xffff0000, v22
	v_mul_f32_e32 v14, v20, v14
	v_mul_f32_e32 v14, v19, v14
	v_cvt_pk_bf16_f32 v14, v18, v14
	v_lshlrev_b32_e32 v18, 16, v15
	v_mul_f32_e32 v20, 0xbfb8aa3b, v18
	v_exp_f32_e32 v20, v20
	v_and_b32_e32 v15, 0xffff0000, v15
	v_mul_f32_e32 v21, 0xbfb8aa3b, v15
	v_exp_f32_e32 v21, v21
	v_add_f32_e32 v20, 1.0, v20
	v_lshlrev_b32_e32 v19, 16, v23
	v_rcp_f32_e32 v20, v20
	v_mul_f32_e32 v18, v19, v18
	v_add_f32_e32 v19, 1.0, v21
	v_rcp_f32_e32 v19, v19
	v_mul_f32_e32 v18, v20, v18
	v_and_b32_e32 v20, 0xffff0000, v23
	v_mul_f32_e32 v15, v20, v15
	v_mul_f32_e32 v15, v19, v15
	v_cvt_pk_bf16_f32 v15, v18, v15
	v_lshlrev_b32_e32 v18, 16, v16
	v_mul_f32_e32 v20, 0xbfb8aa3b, v18
	v_exp_f32_e32 v20, v20
	v_and_b32_e32 v16, 0xffff0000, v16
	v_mul_f32_e32 v21, 0xbfb8aa3b, v16
	v_exp_f32_e32 v21, v21
	v_add_f32_e32 v20, 1.0, v20
	v_lshlrev_b32_e32 v19, 16, v24
	v_rcp_f32_e32 v20, v20
	v_mul_f32_e32 v18, v19, v18
	v_add_f32_e32 v19, 1.0, v21
	v_rcp_f32_e32 v19, v19
	v_mul_f32_e32 v18, v20, v18
	v_and_b32_e32 v20, 0xffff0000, v24
	v_mul_f32_e32 v16, v20, v16
	v_mul_f32_e32 v16, v19, v16
	v_cvt_pk_bf16_f32 v16, v18, v16
	v_lshlrev_b32_e32 v18, 16, v17
	v_mul_f32_e32 v20, 0xbfb8aa3b, v18
	v_exp_f32_e32 v20, v20
	v_and_b32_e32 v17, 0xffff0000, v17
	v_mul_f32_e32 v21, 0xbfb8aa3b, v17
	v_exp_f32_e32 v21, v21
	v_add_f32_e32 v20, 1.0, v20
	v_lshlrev_b32_e32 v19, 16, v25
	v_rcp_f32_e32 v20, v20
	v_mul_f32_e32 v18, v19, v18
	v_add_f32_e32 v19, 1.0, v21
	v_rcp_f32_e32 v19, v19
	v_mul_f32_e32 v18, v20, v18
	v_and_b32_e32 v20, 0xffff0000, v25
	v_mul_f32_e32 v17, v20, v17
	v_mul_f32_e32 v17, v19, v17
	v_cvt_pk_bf16_f32 v17, v18, v17
	global_store_dwordx4 v[32:33], v[14:17], off nt
	ds_read_b128 v[18:21], v0 offset:5440
	s_waitcnt vmcnt(7)
	v_lshlrev_b32_e32 v14, 16, v10
	v_mul_f32_e32 v16, 0xbfb8aa3b, v14
	v_exp_f32_e32 v16, v16
	v_and_b32_e32 v10, 0xffff0000, v10
	v_mul_f32_e32 v17, 0xbfb8aa3b, v10
	v_exp_f32_e32 v17, v17
	v_add_f32_e32 v16, 1.0, v16
	s_waitcnt lgkmcnt(0)
	v_lshlrev_b32_e32 v15, 16, v18
	v_rcp_f32_e32 v16, v16
	v_mul_f32_e32 v14, v15, v14
	v_add_f32_e32 v15, 1.0, v17
	v_rcp_f32_e32 v15, v15
	v_mul_f32_e32 v14, v16, v14
	v_and_b32_e32 v16, 0xffff0000, v18
	v_mul_f32_e32 v10, v16, v10
	v_mul_f32_e32 v10, v15, v10
	v_cvt_pk_bf16_f32 v10, v14, v10
	v_lshlrev_b32_e32 v14, 16, v11
	v_mul_f32_e32 v16, 0xbfb8aa3b, v14
	v_exp_f32_e32 v16, v16
	v_and_b32_e32 v11, 0xffff0000, v11
	v_mul_f32_e32 v17, 0xbfb8aa3b, v11
	v_exp_f32_e32 v17, v17
	v_add_f32_e32 v16, 1.0, v16
	v_lshlrev_b32_e32 v15, 16, v19
	v_rcp_f32_e32 v16, v16
	v_mul_f32_e32 v14, v15, v14
	v_add_f32_e32 v15, 1.0, v17
	v_rcp_f32_e32 v15, v15
	v_mul_f32_e32 v14, v16, v14
	v_and_b32_e32 v16, 0xffff0000, v19
	v_mul_f32_e32 v11, v16, v11
	v_mul_f32_e32 v11, v15, v11
	v_cvt_pk_bf16_f32 v11, v14, v11
	v_lshlrev_b32_e32 v14, 16, v12
	v_mul_f32_e32 v16, 0xbfb8aa3b, v14
	v_exp_f32_e32 v16, v16
	v_and_b32_e32 v12, 0xffff0000, v12
	v_mul_f32_e32 v17, 0xbfb8aa3b, v12
	v_exp_f32_e32 v17, v17
	v_add_f32_e32 v16, 1.0, v16
	v_lshlrev_b32_e32 v15, 16, v20
	v_rcp_f32_e32 v16, v16
	v_mul_f32_e32 v14, v15, v14
	v_add_f32_e32 v15, 1.0, v17
	v_rcp_f32_e32 v15, v15
	v_mul_f32_e32 v14, v16, v14
	v_and_b32_e32 v16, 0xffff0000, v20
	v_mul_f32_e32 v12, v16, v12
	v_mul_f32_e32 v12, v15, v12
	v_cvt_pk_bf16_f32 v12, v14, v12
	v_lshlrev_b32_e32 v14, 16, v13
	v_mul_f32_e32 v16, 0xbfb8aa3b, v14
	v_exp_f32_e32 v16, v16
	v_and_b32_e32 v13, 0xffff0000, v13
	v_mul_f32_e32 v17, 0xbfb8aa3b, v13
	v_exp_f32_e32 v17, v17
	v_add_f32_e32 v16, 1.0, v16
	v_lshlrev_b32_e32 v15, 16, v21
	v_rcp_f32_e32 v16, v16
	v_mul_f32_e32 v14, v15, v14
	v_add_f32_e32 v15, 1.0, v17
	v_rcp_f32_e32 v15, v15
	v_mul_f32_e32 v14, v16, v14
	v_and_b32_e32 v16, 0xffff0000, v21
	v_mul_f32_e32 v13, v16, v13
	v_mul_f32_e32 v13, v15, v13
	v_cvt_pk_bf16_f32 v13, v14, v13
	global_store_dwordx4 v[30:31], v[10:13], off nt
	ds_read_b128 v[14:17], v0 offset:6528
	s_waitcnt vmcnt(7)
; DI unsigned cvtpk(float lo, float hi) { unsigned r; asm volatile("v_cvt_pk_bf16_f32 %0, %1, %2" : "=v"(r) : "v"(lo), "v"(hi)); return r; }
; DI float bflo(unsigned w) { return __uint_as_float(w << 16); }
; DI float bfhi(unsigned w) { return __uint_as_float(w & 0xffff0000u); }
; DI float sigm(float x) { return rcpf_(1.f + ex2(-x * LOG2E)); }
; DI void attn_item(const bf16_t* __restrict__ Qw_, const bf16_t* __restrict__ Kh, const bf16_t* __restrict__ Vh, const bf16_t* Gw, bf16_t* Ow,
;                   int NT, int kt0, int qw, float sinkv, char* lds) {
;     ...
; #pragma unroll
;     for (int k = 0; k < 8; ++k) {
;         const u32x4 ov = *(const u32x4*)(OT + (er + 4 * k) * 136 + ec * 8); u32x4 w;
; #pragma unroll
;         for (int i = 0; i < 4; ++i) { const float g0 = bflo(gv[k][i]), g1 = bfhi(gv[k][i]); w[i] = cvtpk(bflo(ov[i]) * g0 * sigm(g0), bfhi(ov[i]) * g1 * sigm(g1)); }
;         __builtin_nontemporal_store(w, (u32x4*)(Ow + (size_t)(er + 4 * k) * 2048 + ec * 8));
;     }
	v_lshlrev_b32_e32 v10, 16, v6
	v_mul_f32_e32 v12, 0xbfb8aa3b, v10
	v_exp_f32_e32 v12, v12
	v_and_b32_e32 v6, 0xffff0000, v6
	v_mul_f32_e32 v13, 0xbfb8aa3b, v6
	v_exp_f32_e32 v13, v13
	v_add_f32_e32 v12, 1.0, v12
	s_waitcnt lgkmcnt(0)
	v_lshlrev_b32_e32 v11, 16, v14
	v_rcp_f32_e32 v12, v12
	v_mul_f32_e32 v10, v11, v10
	v_add_f32_e32 v11, 1.0, v13
	v_rcp_f32_e32 v11, v11
	v_mul_f32_e32 v10, v12, v10
	v_and_b32_e32 v12, 0xffff0000, v14
	v_mul_f32_e32 v6, v12, v6
	v_mul_f32_e32 v6, v11, v6
	v_cvt_pk_bf16_f32 v6, v10, v6
	v_lshlrev_b32_e32 v10, 16, v7
	v_mul_f32_e32 v12, 0xbfb8aa3b, v10
	v_exp_f32_e32 v12, v12
	v_and_b32_e32 v7, 0xffff0000, v7
	v_mul_f32_e32 v13, 0xbfb8aa3b, v7
	v_exp_f32_e32 v13, v13
	v_add_f32_e32 v12, 1.0, v12
	v_lshlrev_b32_e32 v11, 16, v15
	v_rcp_f32_e32 v12, v12
	v_mul_f32_e32 v10, v11, v10
	v_add_f32_e32 v11, 1.0, v13
	v_rcp_f32_e32 v11, v11
	v_mul_f32_e32 v10, v12, v10
	v_and_b32_e32 v12, 0xffff0000, v15
	v_mul_f32_e32 v7, v12, v7
	v_mul_f32_e32 v7, v11, v7
	v_cvt_pk_bf16_f32 v7, v10, v7
	v_lshlrev_b32_e32 v10, 16, v8
	v_mul_f32_e32 v12, 0xbfb8aa3b, v10
	v_exp_f32_e32 v12, v12
	v_and_b32_e32 v8, 0xffff0000, v8
	v_mul_f32_e32 v13, 0xbfb8aa3b, v8
	v_exp_f32_e32 v13, v13
	v_add_f32_e32 v12, 1.0, v12
	v_lshlrev_b32_e32 v11, 16, v16
	v_rcp_f32_e32 v12, v12
	v_mul_f32_e32 v10, v11, v10
	v_add_f32_e32 v11, 1.0, v13
	v_rcp_f32_e32 v11, v11
	v_mul_f32_e32 v10, v12, v10
	v_and_b32_e32 v12, 0xffff0000, v16
	v_mul_f32_e32 v8, v12, v8
	v_mul_f32_e32 v8, v11, v8
	v_cvt_pk_bf16_f32 v8, v10, v8
	v_lshlrev_b32_e32 v10, 16, v9
	v_mul_f32_e32 v12, 0xbfb8aa3b, v10
	v_exp_f32_e32 v12, v12
	v_and_b32_e32 v9, 0xffff0000, v9
	v_mul_f32_e32 v13, 0xbfb8aa3b, v9
	v_exp_f32_e32 v13, v13
	v_add_f32_e32 v12, 1.0, v12
	v_lshlrev_b32_e32 v11, 16, v17
	v_rcp_f32_e32 v12, v12
	v_mul_f32_e32 v10, v11, v10
	v_add_f32_e32 v11, 1.0, v13
	v_rcp_f32_e32 v11, v11
	v_mul_f32_e32 v10, v12, v10
	v_and_b32_e32 v12, 0xffff0000, v17
	v_mul_f32_e32 v9, v12, v9
	v_mul_f32_e32 v9, v11, v9
	v_cvt_pk_bf16_f32 v9, v10, v9
	ds_read_b128 v[10:13], v0 offset:7616
	s_waitcnt vmcnt(6)
	v_lshlrev_b32_e32 v0, 16, v2
	global_store_dwordx4 v[28:29], v[6:9], off nt
	v_and_b32_e32 v2, 0xffff0000, v2
	s_nop 0
	v_mul_f32_e32 v7, 0xbfb8aa3b, v0
	v_exp_f32_e32 v7, v7
	v_mul_f32_e32 v8, 0xbfb8aa3b, v2
	v_exp_f32_e32 v8, v8
	s_waitcnt lgkmcnt(0)
	v_lshlrev_b32_e32 v6, 16, v10
	v_add_f32_e32 v7, 1.0, v7
	v_rcp_f32_e32 v7, v7
	v_mul_f32_e32 v0, v6, v0
	v_add_f32_e32 v6, 1.0, v8
	v_rcp_f32_e32 v6, v6
	v_mul_f32_e32 v0, v7, v0
	v_and_b32_e32 v7, 0xffff0000, v10
	v_mul_f32_e32 v2, v7, v2
	v_mul_f32_e32 v2, v6, v2
	v_cvt_pk_bf16_f32 v2, v0, v2
	v_lshlrev_b32_e32 v0, 16, v3
	v_mul_f32_e32 v7, 0xbfb8aa3b, v0
	v_exp_f32_e32 v7, v7
	v_and_b32_e32 v3, 0xffff0000, v3
	v_mul_f32_e32 v8, 0xbfb8aa3b, v3
	v_exp_f32_e32 v8, v8
	v_add_f32_e32 v7, 1.0, v7
	v_lshlrev_b32_e32 v6, 16, v11
	v_rcp_f32_e32 v7, v7
	v_mul_f32_e32 v0, v6, v0
	v_add_f32_e32 v6, 1.0, v8
	v_rcp_f32_e32 v6, v6
	v_mul_f32_e32 v0, v7, v0
	v_and_b32_e32 v7, 0xffff0000, v11
	v_mul_f32_e32 v3, v7, v3
	v_mul_f32_e32 v3, v6, v3
	v_cvt_pk_bf16_f32 v3, v0, v3
	v_lshlrev_b32_e32 v0, 16, v4
	v_mul_f32_e32 v7, 0xbfb8aa3b, v0
	v_exp_f32_e32 v7, v7
	v_and_b32_e32 v4, 0xffff0000, v4
	v_mul_f32_e32 v8, 0xbfb8aa3b, v4
	v_exp_f32_e32 v8, v8
	v_add_f32_e32 v7, 1.0, v7
	v_lshlrev_b32_e32 v6, 16, v12
	v_rcp_f32_e32 v7, v7
	v_mul_f32_e32 v0, v6, v0
	v_add_f32_e32 v6, 1.0, v8
	v_rcp_f32_e32 v6, v6
	v_mul_f32_e32 v0, v7, v0
	v_and_b32_e32 v7, 0xffff0000, v12
	v_mul_f32_e32 v4, v7, v4
	v_mul_f32_e32 v4, v6, v4
	v_cvt_pk_bf16_f32 v4, v0, v4
	v_lshlrev_b32_e32 v0, 16, v5
	v_mul_f32_e32 v7, 0xbfb8aa3b, v0
	v_exp_f32_e32 v7, v7
	v_and_b32_e32 v5, 0xffff0000, v5
	v_mul_f32_e32 v8, 0xbfb8aa3b, v5
	v_exp_f32_e32 v8, v8
	v_add_f32_e32 v7, 1.0, v7
	v_lshlrev_b32_e32 v6, 16, v13
	v_rcp_f32_e32 v7, v7
	v_mul_f32_e32 v0, v6, v0
	v_add_f32_e32 v6, 1.0, v8
	v_rcp_f32_e32 v6, v6
	v_mul_f32_e32 v0, v7, v0
	v_and_b32_e32 v7, 0xffff0000, v13
	v_mul_f32_e32 v5, v7, v5
	v_mul_f32_e32 v5, v6, v5
	v_cvt_pk_bf16_f32 v5, v0, v5
	global_store_dwordx4 v[26:27], v[2:5], off nt
	s_cbranch_scc0 .LBB0_265
